# baseline (speedup 1.0000x reference)
.LBB0_1157:
	s_waitcnt vmcnt(3)
	v_lshlrev_b32_e32 v176, 16, v156
	v_and_b32_e32 v177, 0xffff0000, v156
	v_lshlrev_b32_e32 v156, 16, v157
	v_and_b32_e32 v157, 0xffff0000, v157
	v_mov_b32_e32 v180, v177
	v_mov_b32_e32 v181, v157
	v_mov_b32_e32 v178, v176
	v_mov_b32_e32 v179, v156
	v_pk_mul_f32 v[180:181], v[180:181], v[180:181]
	s_waitcnt vmcnt(0)
	v_lshlrev_b32_e32 v198, 16, v145
	v_pk_fma_f32 v[178:179], v[178:179], v[178:179], v[180:181]
	v_lshlrev_b32_e32 v180, 16, v158
	v_and_b32_e32 v181, 0xffff0000, v158
	v_lshlrev_b32_e32 v158, 16, v159
	v_and_b32_e32 v159, 0xffff0000, v159
	v_mov_b32_e32 v184, v159
	v_mov_b32_e32 v185, v181
	v_mov_b32_e32 v182, v158
	v_mov_b32_e32 v183, v180
	v_pk_mul_f32 v[184:185], v[184:185], v[184:185]
	v_pk_add_f32 v[178:179], v[178:179], v[178:179] op_sel:[0,1] op_sel_hi:[1,0]
	v_pk_fma_f32 v[182:183], v[182:183], v[182:183], v[184:185]
	v_and_b32_e32 v199, 0xffff0000, v145
	v_pk_add_f32 v[178:179], v[182:183], v[178:179] op_sel:[1,0] op_sel_hi:[0,1]
	v_pk_add_f32 v[178:179], v[182:183], v[178:179]
	v_lshlrev_b32_e32 v182, 16, v152
	v_and_b32_e32 v183, 0xffff0000, v152
	v_lshlrev_b32_e32 v152, 16, v153
	v_and_b32_e32 v153, 0xffff0000, v153
	v_mov_b32_e32 v186, v183
	v_mov_b32_e32 v187, v153
	v_mov_b32_e32 v184, v182
	v_mov_b32_e32 v185, v152
	v_pk_mul_f32 v[186:187], v[186:187], v[186:187]
	v_and_b32_e32 v195, 0xffff0000, v150
	v_pk_fma_f32 v[184:185], v[184:185], v[184:185], v[186:187]
	v_lshlrev_b32_e32 v186, 16, v154
	v_and_b32_e32 v187, 0xffff0000, v154
	v_lshlrev_b32_e32 v154, 16, v155
	v_and_b32_e32 v155, 0xffff0000, v155
	v_mov_b32_e32 v190, v155
	v_mov_b32_e32 v191, v187
	v_mov_b32_e32 v188, v154
	v_mov_b32_e32 v189, v186
	v_pk_mul_f32 v[190:191], v[190:191], v[190:191]
	v_pk_add_f32 v[184:185], v[184:185], v[184:185] op_sel:[0,1] op_sel_hi:[1,0]
	v_pk_fma_f32 v[188:189], v[188:189], v[188:189], v[190:191]
	v_lshlrev_b32_e32 v196, 16, v144
	v_pk_add_f32 v[184:185], v[188:189], v[184:185] op_sel:[1,0] op_sel_hi:[0,1]
	v_pk_add_f32 v[184:185], v[188:189], v[184:185]
	v_and_b32_e32 v189, 0xffff0000, v148
	v_lshlrev_b32_e32 v188, 16, v148
	v_mul_f32_e32 v148, v189, v189
	v_pk_fma_f32 v[190:191], v[188:189], v[188:189], v[148:149] op_sel_hi:[1,1,0]
	v_lshlrev_b32_e32 v148, 16, v149
	v_and_b32_e32 v149, 0xffff0000, v149
	v_mul_f32_e32 v192, v149, v149
	v_pk_fma_f32 v[192:193], v[148:149], v[148:149], v[192:193] op_sel_hi:[1,1,0]
	v_and_b32_e32 v197, 0xffff0000, v144
	v_pk_mul_f32 v[144:145], v[198:199], v[198:199]
	v_lshlrev_b32_e32 v194, 16, v150
	v_lshlrev_b32_e32 v150, 16, v151
	v_and_b32_e32 v151, 0xffff0000, v151
	v_and_b32_e32 v201, 0xffff0000, v146
	v_mov_b32_e32 v206, v195
	v_mov_b32_e32 v207, v197
	v_mov_b32_e32 v191, v144
	v_mov_b32_e32 v193, v145
	v_lshlrev_b32_e32 v200, 16, v146
	v_lshlrev_b32_e32 v202, 16, v147
	v_and_b32_e32 v203, 0xffff0000, v147
	v_mov_b32_e32 v204, v194
	v_mov_b32_e32 v205, v196
	v_pk_mul_f32 v[206:207], v[206:207], v[206:207]
	v_pk_add_f32 v[144:145], v[190:191], v[192:193]
	v_mov_b32_e32 v192, v151
	v_mov_b32_e32 v193, v201
	v_pk_mul_f32 v[146:147], v[202:203], v[202:203]
	v_pk_fma_f32 v[204:205], v[204:205], v[204:205], v[206:207]
	v_mov_b32_e32 v190, v150
	v_mov_b32_e32 v191, v200
	v_pk_mul_f32 v[192:193], v[192:193], v[192:193]
	v_pk_add_f32 v[144:145], v[204:205], v[144:145]
	v_pk_fma_f32 v[190:191], v[190:191], v[190:191], v[192:193]
	v_mov_b32_e32 v179, v146
	v_mov_b32_e32 v185, v147
	v_pk_add_f32 v[144:145], v[190:191], v[144:145]
	v_pk_add_f32 v[146:147], v[178:179], v[184:185]
	s_nop 0
	v_pk_add_f32 v[144:145], v[146:147], v[144:145]
	s_nop 0
	v_add_f32_e32 v144, v144, v145
	ds_bpermute_b32 v145, v168, v144
	s_waitcnt lgkmcnt(0)
	v_add_f32_e32 v144, v144, v145
	ds_bpermute_b32 v145, v169, v144
	s_waitcnt lgkmcnt(0)
	v_add_f32_e32 v144, v144, v145
	ds_bpermute_b32 v145, v170, v144
	s_waitcnt lgkmcnt(0)
	v_add_f32_e32 v144, v144, v145
	ds_bpermute_b32 v145, v171, v144
	s_waitcnt lgkmcnt(0)
	v_add_f32_e32 v144, v144, v145
	ds_bpermute_b32 v145, v172, v144
	s_waitcnt lgkmcnt(0)
	v_add_f32_e32 v144, v144, v145
	ds_bpermute_b32 v145, v173, v144
	s_waitcnt lgkmcnt(0)
	v_add_f32_e32 v144, v144, v145
	v_fmamk_f32 v144, v144, 0x3a000000, v174
	v_mul_f32_e32 v145, 0x4b800000, v144
	v_cmp_gt_f32_e32 vcc, s42, v144
	s_nop 1
	v_cndmask_b32_e32 v144, v144, v145, vcc
	v_rsq_f32_e32 v144, v144
	s_nop 0
	v_mul_f32_e32 v145, 0x45800000, v144
	v_cndmask_b32_e32 v178, v144, v145, vcc
	v_pk_mul_f32 v[144:145], v[178:179], v[176:177] op_sel_hi:[0,1]
	v_pk_mul_f32 v[146:147], v[178:179], v[156:157] op_sel_hi:[0,1]
	v_add_co_u32_e32 v156, vcc, s43, v164
	v_pk_mul_f32 v[144:145], v[28:29], v[144:145]
	v_pk_mul_f32 v[146:147], v[30:31], v[146:147]
	v_addc_co_u32_e32 v157, vcc, -1, v165, vcc
	global_store_dwordx4 v[156:157], v[144:147], off offset:-2064 nt
	s_andn2_b64 vcc, exec, s[34:35]
	s_nop 0
	v_pk_mul_f32 v[144:145], v[178:179], v[180:181] op_sel_hi:[0,1]
	v_pk_mul_f32 v[146:147], v[178:179], v[158:159] op_sel_hi:[0,1]
	v_pk_mul_f32 v[144:145], v[144:145], v[24:25]
	v_pk_mul_f32 v[146:147], v[146:147], v[26:27]
	global_store_dwordx4 v[156:157], v[144:147], off offset:-2048 nt
	s_nop 1
	v_pk_mul_f32 v[144:145], v[178:179], v[182:183] op_sel_hi:[0,1]
	v_pk_mul_f32 v[146:147], v[178:179], v[152:153] op_sel_hi:[0,1]
	v_pk_mul_f32 v[144:145], v[20:21], v[144:145]
	v_pk_mul_f32 v[146:147], v[22:23], v[146:147]
	global_store_dwordx4 v[156:157], v[144:147], off offset:-16 nt
	s_nop 1
	v_pk_mul_f32 v[144:145], v[178:179], v[186:187] op_sel_hi:[0,1]
	v_pk_mul_f32 v[146:147], v[178:179], v[154:155] op_sel_hi:[0,1]
	v_pk_mul_f32 v[144:145], v[144:145], v[16:17]
	v_pk_mul_f32 v[146:147], v[146:147], v[18:19]
	global_store_dwordx4 v[164:165], v[144:147], off offset:-4096 nt
	s_nop 1
	v_pk_mul_f32 v[144:145], v[178:179], v[188:189] op_sel_hi:[0,1]
	v_pk_mul_f32 v[146:147], v[178:179], v[148:149] op_sel_hi:[0,1]
	v_pk_mul_f32 v[146:147], v[6:7], v[146:147]
	v_pk_mul_f32 v[144:145], v[4:5], v[144:145]
	global_store_dwordx4 v[164:165], v[144:147], off offset:-2064 nt
	s_nop 1
	v_pk_mul_f32 v[144:145], v[178:179], v[194:195] op_sel_hi:[0,1]
	v_pk_mul_f32 v[146:147], v[178:179], v[150:151] op_sel_hi:[0,1]
	v_pk_mul_f32 v[144:145], v[144:145], v[12:13]
	v_pk_mul_f32 v[146:147], v[146:147], v[14:15]
	global_store_dwordx4 v[164:165], v[144:147], off offset:-2048 nt
	s_nop 1
	v_pk_mul_f32 v[144:145], v[178:179], v[196:197] op_sel_hi:[0,1]
	v_pk_mul_f32 v[146:147], v[178:179], v[198:199] op_sel_hi:[0,1]
	v_pk_mul_f32 v[146:147], v[10:11], v[146:147]
	v_pk_mul_f32 v[144:145], v[8:9], v[144:145]
	global_store_dwordx4 v[164:165], v[144:147], off offset:-16 nt
	s_nop 1
	v_pk_mul_f32 v[144:145], v[178:179], v[200:201] op_sel_hi:[0,1]
	v_pk_mul_f32 v[146:147], v[178:179], v[202:203] op_sel_hi:[0,1]
	v_pk_mul_f32 v[146:147], v[146:147], v[2:3]
	v_pk_mul_f32 v[144:145], v[144:145], v[0:1]
	global_store_dwordx4 v[164:165], v[144:147], off nt
	s_cbranch_vccnz .LBB0_1164
	s_nop 0
	v_and_b32_e32 v145, 0xffff0000, v140
	v_and_b32_e32 v147, 0xffff0000, v141
	v_lshlrev_b32_e32 v144, 16, v140
	v_lshlrev_b32_e32 v146, 16, v141
	v_mov_b32_e32 v150, v145
	v_mov_b32_e32 v151, v147
	v_mov_b32_e32 v148, v144
	v_mov_b32_e32 v149, v146
	v_pk_mul_f32 v[150:151], v[150:151], v[150:151]
	v_and_b32_e32 v153, 0xffff0000, v143
	v_pk_fma_f32 v[148:149], v[148:149], v[148:149], v[150:151]
	v_and_b32_e32 v151, 0xffff0000, v142
	v_lshlrev_b32_e32 v150, 16, v142
	v_lshlrev_b32_e32 v152, 16, v143
	v_mov_b32_e32 v156, v153
	v_mov_b32_e32 v157, v151
	v_mov_b32_e32 v154, v152
	v_mov_b32_e32 v155, v150
	v_pk_mul_f32 v[156:157], v[156:157], v[156:157]
	v_pk_add_f32 v[148:149], v[148:149], v[148:149] op_sel:[0,1] op_sel_hi:[1,0]
	v_pk_fma_f32 v[154:155], v[154:155], v[154:155], v[156:157]
	v_and_b32_e32 v157, 0xffff0000, v137
	v_pk_add_f32 v[148:149], v[154:155], v[148:149] op_sel:[1,0] op_sel_hi:[0,1]
	v_pk_add_f32 v[148:149], v[154:155], v[148:149]
	v_and_b32_e32 v155, 0xffff0000, v136
	v_lshlrev_b32_e32 v154, 16, v136
	v_lshlrev_b32_e32 v156, 16, v137
	v_mov_b32_e32 v176, v155
	v_mov_b32_e32 v177, v157
	v_mov_b32_e32 v158, v154
	v_mov_b32_e32 v159, v156
	v_pk_mul_f32 v[176:177], v[176:177], v[176:177]
	v_and_b32_e32 v179, 0xffff0000, v139
	v_pk_fma_f32 v[158:159], v[158:159], v[158:159], v[176:177]
	v_and_b32_e32 v177, 0xffff0000, v138
	v_lshlrev_b32_e32 v176, 16, v138
	v_lshlrev_b32_e32 v178, 16, v139
	v_mov_b32_e32 v182, v179
	v_mov_b32_e32 v183, v177
	v_mov_b32_e32 v180, v178
	v_mov_b32_e32 v181, v176
	v_pk_mul_f32 v[182:183], v[182:183], v[182:183]
	v_pk_add_f32 v[158:159], v[158:159], v[158:159] op_sel:[0,1] op_sel_hi:[1,0]
	v_pk_fma_f32 v[180:181], v[180:181], v[180:181], v[182:183]
	v_and_b32_e32 v185, 0xffff0000, v133
	v_pk_add_f32 v[158:159], v[180:181], v[158:159] op_sel:[1,0] op_sel_hi:[0,1]
	v_pk_add_f32 v[158:159], v[180:181], v[158:159]
	v_and_b32_e32 v181, 0xffff0000, v132
	v_lshlrev_b32_e32 v180, 16, v132
	v_mul_f32_e32 v182, v181, v181
	v_lshlrev_b32_e32 v184, 16, v133
	v_mul_f32_e32 v186, v185, v185
	v_and_b32_e32 v189, 0xffff0000, v134
	v_and_b32_e32 v193, 0xffff0000, v128
	v_lshlrev_b32_e32 v194, 16, v129
	v_and_b32_e32 v195, 0xffff0000, v129
	v_pk_fma_f32 v[182:183], v[180:181], v[180:181], v[182:183] op_sel_hi:[1,1,0]
	v_pk_fma_f32 v[186:187], v[184:185], v[184:185], v[186:187] op_sel_hi:[1,1,0]
	v_lshlrev_b32_e32 v188, 16, v134
	v_and_b32_e32 v191, 0xffff0000, v135
	v_lshlrev_b32_e32 v192, 16, v128
	v_pk_mul_f32 v[196:197], v[194:195], v[194:195]
	v_and_b32_e32 v199, 0xffff0000, v130
	v_mov_b32_e32 v206, v189
	v_mov_b32_e32 v207, v193
	v_lshlrev_b32_e32 v190, 16, v135
	v_lshlrev_b32_e32 v198, 16, v130
	v_lshlrev_b32_e32 v200, 16, v131
	v_and_b32_e32 v201, 0xffff0000, v131
	v_mov_b32_e32 v204, v188
	v_mov_b32_e32 v205, v192
	v_pk_mul_f32 v[206:207], v[206:207], v[206:207]
	v_mov_b32_e32 v183, v196
	v_mov_b32_e32 v187, v197
	v_mov_b32_e32 v196, v191
	v_mov_b32_e32 v197, v199
	v_pk_mul_f32 v[202:203], v[200:201], v[200:201]
	v_pk_fma_f32 v[204:205], v[204:205], v[204:205], v[206:207]
	v_pk_add_f32 v[182:183], v[182:183], v[186:187]
	v_mov_b32_e32 v186, v190
	v_mov_b32_e32 v187, v198
	v_pk_mul_f32 v[196:197], v[196:197], v[196:197]
	v_pk_add_f32 v[182:183], v[204:205], v[182:183]
	v_pk_fma_f32 v[186:187], v[186:187], v[186:187], v[196:197]
	v_mov_b32_e32 v149, v202
	v_mov_b32_e32 v159, v203
	v_pk_add_f32 v[182:183], v[186:187], v[182:183]
	v_pk_add_f32 v[148:149], v[148:149], v[158:159]
	s_ashr_i32 s31, s30, 31
	v_pk_add_f32 v[148:149], v[148:149], v[182:183]
	s_lshl_b64 s[30:31], s[30:31], 13
	v_add_f32_e32 v148, v148, v149
	ds_bpermute_b32 v149, v168, v148
	s_waitcnt lgkmcnt(0)
	v_add_f32_e32 v148, v148, v149
	ds_bpermute_b32 v149, v169, v148
	s_waitcnt lgkmcnt(0)
	v_add_f32_e32 v148, v148, v149
	ds_bpermute_b32 v149, v170, v148
	s_waitcnt lgkmcnt(0)
	v_add_f32_e32 v148, v148, v149
	ds_bpermute_b32 v149, v171, v148
	s_waitcnt lgkmcnt(0)
	v_add_f32_e32 v148, v148, v149
	ds_bpermute_b32 v149, v172, v148
	s_waitcnt lgkmcnt(0)
	v_add_f32_e32 v148, v148, v149
	ds_bpermute_b32 v149, v173, v148
	s_waitcnt lgkmcnt(0)
	v_add_f32_e32 v148, v148, v149
	v_fmamk_f32 v148, v148, 0x3a000000, v174
	v_mul_f32_e32 v149, 0x4b800000, v148
	v_cmp_gt_f32_e32 vcc, s42, v148
	s_nop 1
	v_cndmask_b32_e32 v148, v148, v149, vcc
	v_rsq_f32_e32 v158, v148
	v_lshl_add_u64 v[148:149], v[162:163], 0, s[30:31]
	v_mul_f32_e32 v159, 0x45800000, v158
	v_cndmask_b32_e32 v158, v158, v159, vcc
	v_pk_mul_f32 v[144:145], v[158:159], v[144:145] op_sel_hi:[0,1]
	v_pk_mul_f32 v[146:147], v[158:159], v[146:147] op_sel_hi:[0,1]
	v_pk_mul_f32 v[144:145], v[28:29], v[144:145]
	v_pk_mul_f32 v[146:147], v[30:31], v[146:147]
	global_store_dwordx4 v[148:149], v[144:147], off nt
	s_nop 1
	v_pk_mul_f32 v[144:145], v[158:159], v[150:151] op_sel_hi:[0,1]
	v_pk_mul_f32 v[146:147], v[158:159], v[152:153] op_sel_hi:[0,1]
	v_pk_mul_f32 v[144:145], v[144:145], v[24:25]
	v_pk_mul_f32 v[146:147], v[146:147], v[26:27]
	global_store_dwordx4 v[148:149], v[144:147], off offset:16 nt
	s_nop 1
	v_pk_mul_f32 v[144:145], v[158:159], v[154:155] op_sel_hi:[0,1]
	v_pk_mul_f32 v[146:147], v[158:159], v[156:157] op_sel_hi:[0,1]
	v_pk_mul_f32 v[144:145], v[20:21], v[144:145]
	v_pk_mul_f32 v[146:147], v[22:23], v[146:147]
	global_store_dwordx4 v[148:149], v[144:147], off offset:2048 nt
	s_nop 1
	v_pk_mul_f32 v[144:145], v[158:159], v[176:177] op_sel_hi:[0,1]
	v_pk_mul_f32 v[146:147], v[158:159], v[178:179] op_sel_hi:[0,1]
	v_pk_mul_f32 v[144:145], v[144:145], v[16:17]
	v_pk_mul_f32 v[146:147], v[146:147], v[18:19]
	global_store_dwordx4 v[148:149], v[144:147], off offset:2064 nt
	v_add_co_u32_e32 v148, vcc, s33, v148
	s_nop 0
	v_pk_mul_f32 v[144:145], v[158:159], v[180:181] op_sel_hi:[0,1]
	v_pk_mul_f32 v[146:147], v[158:159], v[184:185] op_sel_hi:[0,1]
	v_pk_mul_f32 v[146:147], v[6:7], v[146:147]
	v_pk_mul_f32 v[144:145], v[4:5], v[144:145]
	v_addc_co_u32_e32 v149, vcc, 0, v149, vcc
	global_store_dwordx4 v[148:149], v[144:147], off nt
	s_nop 1
	v_pk_mul_f32 v[144:145], v[158:159], v[188:189] op_sel_hi:[0,1]
	v_pk_mul_f32 v[146:147], v[158:159], v[190:191] op_sel_hi:[0,1]
	v_pk_mul_f32 v[144:145], v[144:145], v[12:13]
	v_pk_mul_f32 v[146:147], v[146:147], v[14:15]
	global_store_dwordx4 v[148:149], v[144:147], off offset:16 nt
	s_nop 1
	v_pk_mul_f32 v[144:145], v[158:159], v[192:193] op_sel_hi:[0,1]
	v_pk_mul_f32 v[146:147], v[158:159], v[194:195] op_sel_hi:[0,1]
	v_pk_mul_f32 v[146:147], v[10:11], v[146:147]
	v_pk_mul_f32 v[144:145], v[8:9], v[144:145]
	global_store_dwordx4 v[148:149], v[144:147], off offset:2048 nt
	s_nop 1
	v_pk_mul_f32 v[144:145], v[158:159], v[198:199] op_sel_hi:[0,1]
	v_pk_mul_f32 v[146:147], v[158:159], v[200:201] op_sel_hi:[0,1]
	v_pk_mul_f32 v[146:147], v[146:147], v[2:3]
	v_pk_mul_f32 v[144:145], v[144:145], v[0:1]
	global_store_dwordx4 v[148:149], v[144:147], off offset:2064 nt
	s_andn2_b64 vcc, exec, s[28:29]
	s_cbranch_vccz .LBB0_1165

.LBB0_1160:
	v_and_b32_e32 v145, 0xffff0000, v108
	v_and_b32_e32 v147, 0xffff0000, v109
	v_lshlrev_b32_e32 v144, 16, v108
	v_lshlrev_b32_e32 v146, 16, v109
	v_mov_b32_e32 v150, v145
	v_mov_b32_e32 v151, v147
	v_mov_b32_e32 v148, v144
	v_mov_b32_e32 v149, v146
	v_pk_mul_f32 v[150:151], v[150:151], v[150:151]
	v_and_b32_e32 v153, 0xffff0000, v111
	v_pk_fma_f32 v[148:149], v[148:149], v[148:149], v[150:151]
	v_and_b32_e32 v151, 0xffff0000, v110
	v_lshlrev_b32_e32 v150, 16, v110
	v_lshlrev_b32_e32 v152, 16, v111
	v_mov_b32_e32 v156, v153
	v_mov_b32_e32 v157, v151
	v_mov_b32_e32 v154, v152
	v_mov_b32_e32 v155, v150
	v_pk_mul_f32 v[156:157], v[156:157], v[156:157]
	v_pk_add_f32 v[148:149], v[148:149], v[148:149] op_sel:[0,1] op_sel_hi:[1,0]
	v_pk_fma_f32 v[154:155], v[154:155], v[154:155], v[156:157]
	v_and_b32_e32 v157, 0xffff0000, v105
	v_pk_add_f32 v[148:149], v[154:155], v[148:149] op_sel:[1,0] op_sel_hi:[0,1]
	v_pk_add_f32 v[148:149], v[154:155], v[148:149]
	v_and_b32_e32 v155, 0xffff0000, v104
	v_lshlrev_b32_e32 v154, 16, v104
	v_lshlrev_b32_e32 v156, 16, v105
	v_mov_b32_e32 v176, v155
	v_mov_b32_e32 v177, v157
	v_mov_b32_e32 v158, v154
	v_mov_b32_e32 v159, v156
	v_pk_mul_f32 v[176:177], v[176:177], v[176:177]
	v_and_b32_e32 v179, 0xffff0000, v107
	v_pk_fma_f32 v[158:159], v[158:159], v[158:159], v[176:177]
	v_and_b32_e32 v177, 0xffff0000, v106
	v_lshlrev_b32_e32 v176, 16, v106
	v_lshlrev_b32_e32 v178, 16, v107
	v_mov_b32_e32 v182, v179
	v_mov_b32_e32 v183, v177
	v_mov_b32_e32 v180, v178
	v_mov_b32_e32 v181, v176
	v_pk_mul_f32 v[182:183], v[182:183], v[182:183]
	v_pk_add_f32 v[158:159], v[158:159], v[158:159] op_sel:[0,1] op_sel_hi:[1,0]
	v_pk_fma_f32 v[180:181], v[180:181], v[180:181], v[182:183]
	v_and_b32_e32 v185, 0xffff0000, v101
	v_pk_add_f32 v[158:159], v[180:181], v[158:159] op_sel:[1,0] op_sel_hi:[0,1]
	v_pk_add_f32 v[158:159], v[180:181], v[158:159]
	v_and_b32_e32 v181, 0xffff0000, v100
	v_lshlrev_b32_e32 v180, 16, v100
	v_mul_f32_e32 v182, v181, v181
	v_lshlrev_b32_e32 v184, 16, v101
	v_mul_f32_e32 v186, v185, v185
	v_and_b32_e32 v189, 0xffff0000, v102
	v_and_b32_e32 v193, 0xffff0000, v96
	v_lshlrev_b32_e32 v194, 16, v97
	v_and_b32_e32 v195, 0xffff0000, v97
	v_pk_fma_f32 v[182:183], v[180:181], v[180:181], v[182:183] op_sel_hi:[1,1,0]
	v_pk_fma_f32 v[186:187], v[184:185], v[184:185], v[186:187] op_sel_hi:[1,1,0]
	v_lshlrev_b32_e32 v188, 16, v102
	v_and_b32_e32 v191, 0xffff0000, v103
	v_lshlrev_b32_e32 v192, 16, v96
	v_pk_mul_f32 v[196:197], v[194:195], v[194:195]
	v_and_b32_e32 v199, 0xffff0000, v98
	v_mov_b32_e32 v206, v189
	v_mov_b32_e32 v207, v193
	v_lshlrev_b32_e32 v190, 16, v103
	v_lshlrev_b32_e32 v198, 16, v98
	v_lshlrev_b32_e32 v200, 16, v99
	v_and_b32_e32 v201, 0xffff0000, v99
	v_mov_b32_e32 v204, v188
	v_mov_b32_e32 v205, v192
	v_pk_mul_f32 v[206:207], v[206:207], v[206:207]
	v_mov_b32_e32 v183, v196
	v_mov_b32_e32 v187, v197
	v_mov_b32_e32 v196, v191
	v_mov_b32_e32 v197, v199
	v_pk_mul_f32 v[202:203], v[200:201], v[200:201]
	v_pk_fma_f32 v[204:205], v[204:205], v[204:205], v[206:207]
	v_pk_add_f32 v[182:183], v[182:183], v[186:187]
	v_mov_b32_e32 v186, v190
	v_mov_b32_e32 v187, v198
	v_pk_mul_f32 v[196:197], v[196:197], v[196:197]
	v_pk_add_f32 v[182:183], v[204:205], v[182:183]
	v_pk_fma_f32 v[186:187], v[186:187], v[186:187], v[196:197]
	v_mov_b32_e32 v149, v202
	v_mov_b32_e32 v159, v203
	v_pk_add_f32 v[182:183], v[186:187], v[182:183]
	v_pk_add_f32 v[148:149], v[148:149], v[158:159]
	s_ashr_i32 s23, s22, 31
	v_pk_add_f32 v[148:149], v[148:149], v[182:183]
	s_lshl_b64 s[22:23], s[22:23], 13
	v_add_f32_e32 v148, v148, v149
	ds_bpermute_b32 v149, v168, v148
	s_waitcnt lgkmcnt(0)
	v_add_f32_e32 v148, v148, v149
	ds_bpermute_b32 v149, v169, v148
	s_waitcnt lgkmcnt(0)
	v_add_f32_e32 v148, v148, v149
	ds_bpermute_b32 v149, v170, v148
	s_waitcnt lgkmcnt(0)
	v_add_f32_e32 v148, v148, v149
	ds_bpermute_b32 v149, v171, v148
	s_waitcnt lgkmcnt(0)
	v_add_f32_e32 v148, v148, v149
	ds_bpermute_b32 v149, v172, v148
	s_waitcnt lgkmcnt(0)
	v_add_f32_e32 v148, v148, v149
	ds_bpermute_b32 v149, v173, v148
	s_waitcnt lgkmcnt(0)
	v_add_f32_e32 v148, v148, v149
	v_fmamk_f32 v148, v148, 0x3a000000, v174
	v_mul_f32_e32 v149, 0x4b800000, v148
	v_cmp_gt_f32_e32 vcc, s42, v148
	s_nop 1
	v_cndmask_b32_e32 v148, v148, v149, vcc
	v_rsq_f32_e32 v158, v148
	v_lshl_add_u64 v[148:149], v[162:163], 0, s[22:23]
	v_mul_f32_e32 v159, 0x45800000, v158
	v_cndmask_b32_e32 v158, v158, v159, vcc
	v_pk_mul_f32 v[144:145], v[158:159], v[144:145] op_sel_hi:[0,1]
	v_pk_mul_f32 v[146:147], v[158:159], v[146:147] op_sel_hi:[0,1]
	v_pk_mul_f32 v[144:145], v[28:29], v[144:145]
	v_pk_mul_f32 v[146:147], v[30:31], v[146:147]
	global_store_dwordx4 v[148:149], v[144:147], off nt
	s_nop 1
	v_pk_mul_f32 v[144:145], v[158:159], v[150:151] op_sel_hi:[0,1]
	v_pk_mul_f32 v[146:147], v[158:159], v[152:153] op_sel_hi:[0,1]
	v_pk_mul_f32 v[144:145], v[144:145], v[24:25]
	v_pk_mul_f32 v[146:147], v[146:147], v[26:27]
	global_store_dwordx4 v[148:149], v[144:147], off offset:16 nt
	s_nop 1
	v_pk_mul_f32 v[144:145], v[158:159], v[154:155] op_sel_hi:[0,1]
	v_pk_mul_f32 v[146:147], v[158:159], v[156:157] op_sel_hi:[0,1]
	v_pk_mul_f32 v[144:145], v[20:21], v[144:145]
	v_pk_mul_f32 v[146:147], v[22:23], v[146:147]
	global_store_dwordx4 v[148:149], v[144:147], off offset:2048 nt
	s_nop 1
	v_pk_mul_f32 v[144:145], v[158:159], v[176:177] op_sel_hi:[0,1]
	v_pk_mul_f32 v[146:147], v[158:159], v[178:179] op_sel_hi:[0,1]
	v_pk_mul_f32 v[144:145], v[144:145], v[16:17]
	v_pk_mul_f32 v[146:147], v[146:147], v[18:19]
	global_store_dwordx4 v[148:149], v[144:147], off offset:2064 nt
	v_add_co_u32_e32 v148, vcc, s33, v148
	s_nop 0
	v_pk_mul_f32 v[144:145], v[158:159], v[180:181] op_sel_hi:[0,1]
	v_pk_mul_f32 v[146:147], v[158:159], v[184:185] op_sel_hi:[0,1]
	v_pk_mul_f32 v[146:147], v[6:7], v[146:147]
	v_pk_mul_f32 v[144:145], v[4:5], v[144:145]
	v_addc_co_u32_e32 v149, vcc, 0, v149, vcc
	global_store_dwordx4 v[148:149], v[144:147], off nt
	s_nop 1
	v_pk_mul_f32 v[144:145], v[158:159], v[188:189] op_sel_hi:[0,1]
	v_pk_mul_f32 v[146:147], v[158:159], v[190:191] op_sel_hi:[0,1]
	v_pk_mul_f32 v[144:145], v[144:145], v[12:13]
	v_pk_mul_f32 v[146:147], v[146:147], v[14:15]
	global_store_dwordx4 v[148:149], v[144:147], off offset:16 nt
	s_nop 1
	v_pk_mul_f32 v[144:145], v[158:159], v[192:193] op_sel_hi:[0,1]
	v_pk_mul_f32 v[146:147], v[158:159], v[194:195] op_sel_hi:[0,1]
	v_pk_mul_f32 v[146:147], v[10:11], v[146:147]
	v_pk_mul_f32 v[144:145], v[8:9], v[144:145]
	global_store_dwordx4 v[148:149], v[144:147], off offset:2048 nt
	s_nop 1
	v_pk_mul_f32 v[144:145], v[158:159], v[198:199] op_sel_hi:[0,1]
	v_pk_mul_f32 v[146:147], v[158:159], v[200:201] op_sel_hi:[0,1]
	v_pk_mul_f32 v[146:147], v[146:147], v[2:3]
	v_pk_mul_f32 v[144:145], v[144:145], v[0:1]
	global_store_dwordx4 v[148:149], v[144:147], off offset:2064 nt
	s_andn2_b64 vcc, exec, s[20:21]
	s_cbranch_vccz .LBB0_1167

.LBB0_1162:
	v_and_b32_e32 v145, 0xffff0000, v76
	v_and_b32_e32 v147, 0xffff0000, v77
	v_lshlrev_b32_e32 v144, 16, v76
	v_lshlrev_b32_e32 v146, 16, v77
	v_mov_b32_e32 v150, v145
	v_mov_b32_e32 v151, v147
	v_mov_b32_e32 v148, v144
	v_mov_b32_e32 v149, v146
	v_pk_mul_f32 v[150:151], v[150:151], v[150:151]
	v_and_b32_e32 v153, 0xffff0000, v79
	v_pk_fma_f32 v[148:149], v[148:149], v[148:149], v[150:151]
	v_and_b32_e32 v151, 0xffff0000, v78
	v_lshlrev_b32_e32 v150, 16, v78
	v_lshlrev_b32_e32 v152, 16, v79
	v_mov_b32_e32 v156, v153
	v_mov_b32_e32 v157, v151
	v_mov_b32_e32 v154, v152
	v_mov_b32_e32 v155, v150
	v_pk_mul_f32 v[156:157], v[156:157], v[156:157]
	v_pk_add_f32 v[148:149], v[148:149], v[148:149] op_sel:[0,1] op_sel_hi:[1,0]
	v_pk_fma_f32 v[154:155], v[154:155], v[154:155], v[156:157]
	v_and_b32_e32 v157, 0xffff0000, v73
	v_pk_add_f32 v[148:149], v[154:155], v[148:149] op_sel:[1,0] op_sel_hi:[0,1]
	v_pk_add_f32 v[148:149], v[154:155], v[148:149]
	v_and_b32_e32 v155, 0xffff0000, v72
	v_lshlrev_b32_e32 v154, 16, v72
	v_lshlrev_b32_e32 v156, 16, v73
	v_mov_b32_e32 v176, v155
	v_mov_b32_e32 v177, v157
	v_mov_b32_e32 v158, v154
	v_mov_b32_e32 v159, v156
	v_pk_mul_f32 v[176:177], v[176:177], v[176:177]
	v_and_b32_e32 v179, 0xffff0000, v75
	v_pk_fma_f32 v[158:159], v[158:159], v[158:159], v[176:177]
	v_and_b32_e32 v177, 0xffff0000, v74
	v_lshlrev_b32_e32 v176, 16, v74
	v_lshlrev_b32_e32 v178, 16, v75
	v_mov_b32_e32 v182, v179
	v_mov_b32_e32 v183, v177
	v_mov_b32_e32 v180, v178
	v_mov_b32_e32 v181, v176
	v_pk_mul_f32 v[182:183], v[182:183], v[182:183]
	v_pk_add_f32 v[158:159], v[158:159], v[158:159] op_sel:[0,1] op_sel_hi:[1,0]
	v_pk_fma_f32 v[180:181], v[180:181], v[180:181], v[182:183]
	v_and_b32_e32 v185, 0xffff0000, v69
	v_pk_add_f32 v[158:159], v[180:181], v[158:159] op_sel:[1,0] op_sel_hi:[0,1]
	v_pk_add_f32 v[158:159], v[180:181], v[158:159]
	v_and_b32_e32 v181, 0xffff0000, v68
	v_lshlrev_b32_e32 v180, 16, v68
	v_mul_f32_e32 v182, v181, v181
	v_lshlrev_b32_e32 v184, 16, v69
	v_mul_f32_e32 v186, v185, v185
	v_and_b32_e32 v189, 0xffff0000, v70
	v_and_b32_e32 v193, 0xffff0000, v64
	v_lshlrev_b32_e32 v194, 16, v65
	v_and_b32_e32 v195, 0xffff0000, v65
	v_pk_fma_f32 v[182:183], v[180:181], v[180:181], v[182:183] op_sel_hi:[1,1,0]
	v_pk_fma_f32 v[186:187], v[184:185], v[184:185], v[186:187] op_sel_hi:[1,1,0]
	v_lshlrev_b32_e32 v188, 16, v70
	v_and_b32_e32 v191, 0xffff0000, v71
	v_lshlrev_b32_e32 v192, 16, v64
	v_pk_mul_f32 v[196:197], v[194:195], v[194:195]
	v_and_b32_e32 v199, 0xffff0000, v66
	v_mov_b32_e32 v206, v189
	v_mov_b32_e32 v207, v193
	v_lshlrev_b32_e32 v190, 16, v71
	v_lshlrev_b32_e32 v198, 16, v66
	v_lshlrev_b32_e32 v200, 16, v67
	v_and_b32_e32 v201, 0xffff0000, v67
	v_mov_b32_e32 v204, v188
	v_mov_b32_e32 v205, v192
	v_pk_mul_f32 v[206:207], v[206:207], v[206:207]
	v_mov_b32_e32 v183, v196
	v_mov_b32_e32 v187, v197
	v_mov_b32_e32 v196, v191
	v_mov_b32_e32 v197, v199
	v_pk_mul_f32 v[202:203], v[200:201], v[200:201]
	v_pk_fma_f32 v[204:205], v[204:205], v[204:205], v[206:207]
	v_pk_add_f32 v[182:183], v[182:183], v[186:187]
	v_mov_b32_e32 v186, v190
	v_mov_b32_e32 v187, v198
	v_pk_mul_f32 v[196:197], v[196:197], v[196:197]
	v_pk_add_f32 v[182:183], v[204:205], v[182:183]
	v_pk_fma_f32 v[186:187], v[186:187], v[186:187], v[196:197]
	v_mov_b32_e32 v149, v202
	v_mov_b32_e32 v159, v203
	v_pk_add_f32 v[182:183], v[186:187], v[182:183]
	v_pk_add_f32 v[148:149], v[148:149], v[158:159]
	s_ashr_i32 s15, s14, 31
	v_pk_add_f32 v[148:149], v[148:149], v[182:183]
	s_lshl_b64 s[14:15], s[14:15], 13
	v_add_f32_e32 v148, v148, v149
	ds_bpermute_b32 v149, v168, v148
	s_waitcnt lgkmcnt(0)
	v_add_f32_e32 v148, v148, v149
	ds_bpermute_b32 v149, v169, v148
	s_waitcnt lgkmcnt(0)
	v_add_f32_e32 v148, v148, v149
	ds_bpermute_b32 v149, v170, v148
	s_waitcnt lgkmcnt(0)
	v_add_f32_e32 v148, v148, v149
	ds_bpermute_b32 v149, v171, v148
	s_waitcnt lgkmcnt(0)
	v_add_f32_e32 v148, v148, v149
	ds_bpermute_b32 v149, v172, v148
	s_waitcnt lgkmcnt(0)
	v_add_f32_e32 v148, v148, v149
	ds_bpermute_b32 v149, v173, v148
	s_waitcnt lgkmcnt(0)
	v_add_f32_e32 v148, v148, v149
	v_fmamk_f32 v148, v148, 0x3a000000, v174
	v_mul_f32_e32 v149, 0x4b800000, v148
	v_cmp_gt_f32_e32 vcc, s42, v148
	s_nop 1
	v_cndmask_b32_e32 v148, v148, v149, vcc
	v_rsq_f32_e32 v158, v148
	v_lshl_add_u64 v[148:149], v[162:163], 0, s[14:15]
	v_mul_f32_e32 v159, 0x45800000, v158
	v_cndmask_b32_e32 v158, v158, v159, vcc
	v_pk_mul_f32 v[144:145], v[158:159], v[144:145] op_sel_hi:[0,1]
	v_pk_mul_f32 v[146:147], v[158:159], v[146:147] op_sel_hi:[0,1]
	v_pk_mul_f32 v[144:145], v[28:29], v[144:145]
	v_pk_mul_f32 v[146:147], v[30:31], v[146:147]
	global_store_dwordx4 v[148:149], v[144:147], off nt
	s_nop 1
	v_pk_mul_f32 v[144:145], v[158:159], v[150:151] op_sel_hi:[0,1]
	v_pk_mul_f32 v[146:147], v[158:159], v[152:153] op_sel_hi:[0,1]
	v_pk_mul_f32 v[144:145], v[144:145], v[24:25]
	v_pk_mul_f32 v[146:147], v[146:147], v[26:27]
	global_store_dwordx4 v[148:149], v[144:147], off offset:16 nt
	s_nop 1
	v_pk_mul_f32 v[144:145], v[158:159], v[154:155] op_sel_hi:[0,1]
	v_pk_mul_f32 v[146:147], v[158:159], v[156:157] op_sel_hi:[0,1]
	v_pk_mul_f32 v[144:145], v[20:21], v[144:145]
	v_pk_mul_f32 v[146:147], v[22:23], v[146:147]
	global_store_dwordx4 v[148:149], v[144:147], off offset:2048 nt
	s_nop 1
	v_pk_mul_f32 v[144:145], v[158:159], v[176:177] op_sel_hi:[0,1]
	v_pk_mul_f32 v[146:147], v[158:159], v[178:179] op_sel_hi:[0,1]
	v_pk_mul_f32 v[144:145], v[144:145], v[16:17]
	v_pk_mul_f32 v[146:147], v[146:147], v[18:19]
	global_store_dwordx4 v[148:149], v[144:147], off offset:2064 nt
	v_add_co_u32_e32 v148, vcc, s33, v148
	s_nop 0
	v_pk_mul_f32 v[144:145], v[158:159], v[180:181] op_sel_hi:[0,1]
	v_pk_mul_f32 v[146:147], v[158:159], v[184:185] op_sel_hi:[0,1]
	v_pk_mul_f32 v[146:147], v[6:7], v[146:147]
	v_pk_mul_f32 v[144:145], v[4:5], v[144:145]
	v_addc_co_u32_e32 v149, vcc, 0, v149, vcc
	global_store_dwordx4 v[148:149], v[144:147], off nt
	s_nop 1
	v_pk_mul_f32 v[144:145], v[158:159], v[188:189] op_sel_hi:[0,1]
	v_pk_mul_f32 v[146:147], v[158:159], v[190:191] op_sel_hi:[0,1]
	v_pk_mul_f32 v[144:145], v[144:145], v[12:13]
	v_pk_mul_f32 v[146:147], v[146:147], v[14:15]
	global_store_dwordx4 v[148:149], v[144:147], off offset:16 nt
	s_nop 1
	v_pk_mul_f32 v[144:145], v[158:159], v[192:193] op_sel_hi:[0,1]
	v_pk_mul_f32 v[146:147], v[158:159], v[194:195] op_sel_hi:[0,1]
	v_pk_mul_f32 v[146:147], v[10:11], v[146:147]
	v_pk_mul_f32 v[144:145], v[8:9], v[144:145]
	global_store_dwordx4 v[148:149], v[144:147], off offset:2048 nt
	s_nop 1
	v_pk_mul_f32 v[144:145], v[158:159], v[198:199] op_sel_hi:[0,1]
	v_pk_mul_f32 v[146:147], v[158:159], v[200:201] op_sel_hi:[0,1]
	v_pk_mul_f32 v[146:147], v[146:147], v[2:3]
	v_pk_mul_f32 v[144:145], v[144:145], v[0:1]
	global_store_dwordx4 v[148:149], v[144:147], off offset:2064 nt
	s_andn2_b64 vcc, exec, s[12:13]
	s_cbranch_vccz .LBB0_1169

.LBB0_1165:
	v_and_b32_e32 v145, 0xffff0000, v124
	v_and_b32_e32 v147, 0xffff0000, v125
	v_lshlrev_b32_e32 v144, 16, v124
	v_lshlrev_b32_e32 v146, 16, v125
	v_mov_b32_e32 v150, v145
	v_mov_b32_e32 v151, v147
	v_mov_b32_e32 v148, v144
	v_mov_b32_e32 v149, v146
	v_pk_mul_f32 v[150:151], v[150:151], v[150:151]
	v_and_b32_e32 v153, 0xffff0000, v127
	v_pk_fma_f32 v[148:149], v[148:149], v[148:149], v[150:151]
	v_and_b32_e32 v151, 0xffff0000, v126
	v_lshlrev_b32_e32 v150, 16, v126
	v_lshlrev_b32_e32 v152, 16, v127
	v_mov_b32_e32 v156, v153
	v_mov_b32_e32 v157, v151
	v_mov_b32_e32 v154, v152
	v_mov_b32_e32 v155, v150
	v_pk_mul_f32 v[156:157], v[156:157], v[156:157]
	v_pk_add_f32 v[148:149], v[148:149], v[148:149] op_sel:[0,1] op_sel_hi:[1,0]
	v_pk_fma_f32 v[154:155], v[154:155], v[154:155], v[156:157]
	v_and_b32_e32 v157, 0xffff0000, v121
	v_pk_add_f32 v[148:149], v[154:155], v[148:149] op_sel:[1,0] op_sel_hi:[0,1]
	v_pk_add_f32 v[148:149], v[154:155], v[148:149]
	v_and_b32_e32 v155, 0xffff0000, v120
	v_lshlrev_b32_e32 v154, 16, v120
	v_lshlrev_b32_e32 v156, 16, v121
	v_mov_b32_e32 v176, v155
	v_mov_b32_e32 v177, v157
	v_mov_b32_e32 v158, v154
	v_mov_b32_e32 v159, v156
	v_pk_mul_f32 v[176:177], v[176:177], v[176:177]
	v_and_b32_e32 v179, 0xffff0000, v123
	v_pk_fma_f32 v[158:159], v[158:159], v[158:159], v[176:177]
	v_and_b32_e32 v177, 0xffff0000, v122
	v_lshlrev_b32_e32 v176, 16, v122
	v_lshlrev_b32_e32 v178, 16, v123
	v_mov_b32_e32 v182, v179
	v_mov_b32_e32 v183, v177
	v_mov_b32_e32 v180, v178
	v_mov_b32_e32 v181, v176
	v_pk_mul_f32 v[182:183], v[182:183], v[182:183]
	v_pk_add_f32 v[158:159], v[158:159], v[158:159] op_sel:[0,1] op_sel_hi:[1,0]
	v_pk_fma_f32 v[180:181], v[180:181], v[180:181], v[182:183]
	v_and_b32_e32 v185, 0xffff0000, v117
	v_pk_add_f32 v[158:159], v[180:181], v[158:159] op_sel:[1,0] op_sel_hi:[0,1]
	v_pk_add_f32 v[158:159], v[180:181], v[158:159]
	v_and_b32_e32 v181, 0xffff0000, v116
	v_lshlrev_b32_e32 v180, 16, v116
	v_mul_f32_e32 v182, v181, v181
	v_lshlrev_b32_e32 v184, 16, v117
	v_mul_f32_e32 v186, v185, v185
	v_and_b32_e32 v189, 0xffff0000, v118
	v_and_b32_e32 v193, 0xffff0000, v112
	v_lshlrev_b32_e32 v194, 16, v113
	v_and_b32_e32 v195, 0xffff0000, v113
	v_pk_fma_f32 v[182:183], v[180:181], v[180:181], v[182:183] op_sel_hi:[1,1,0]
	v_pk_fma_f32 v[186:187], v[184:185], v[184:185], v[186:187] op_sel_hi:[1,1,0]
	v_lshlrev_b32_e32 v188, 16, v118
	v_and_b32_e32 v191, 0xffff0000, v119
	v_lshlrev_b32_e32 v192, 16, v112
	v_pk_mul_f32 v[196:197], v[194:195], v[194:195]
	v_and_b32_e32 v199, 0xffff0000, v114
	v_mov_b32_e32 v206, v189
	v_mov_b32_e32 v207, v193
	v_lshlrev_b32_e32 v190, 16, v119
	v_lshlrev_b32_e32 v198, 16, v114
	v_lshlrev_b32_e32 v200, 16, v115
	v_and_b32_e32 v201, 0xffff0000, v115
	v_mov_b32_e32 v204, v188
	v_mov_b32_e32 v205, v192
	v_pk_mul_f32 v[206:207], v[206:207], v[206:207]
	v_mov_b32_e32 v183, v196
	v_mov_b32_e32 v187, v197
	v_mov_b32_e32 v196, v191
	v_mov_b32_e32 v197, v199
	v_pk_mul_f32 v[202:203], v[200:201], v[200:201]
	v_pk_fma_f32 v[204:205], v[204:205], v[204:205], v[206:207]
	v_pk_add_f32 v[182:183], v[182:183], v[186:187]
	v_mov_b32_e32 v186, v190
	v_mov_b32_e32 v187, v198
	v_pk_mul_f32 v[196:197], v[196:197], v[196:197]
	v_pk_add_f32 v[182:183], v[204:205], v[182:183]
	v_pk_fma_f32 v[186:187], v[186:187], v[186:187], v[196:197]
	v_mov_b32_e32 v149, v202
	v_mov_b32_e32 v159, v203
	v_pk_add_f32 v[182:183], v[186:187], v[182:183]
	v_pk_add_f32 v[148:149], v[148:149], v[158:159]
	s_ashr_i32 s27, s26, 31
	v_pk_add_f32 v[148:149], v[148:149], v[182:183]
	s_lshl_b64 s[26:27], s[26:27], 13
	v_add_f32_e32 v148, v148, v149
	ds_bpermute_b32 v149, v168, v148
	s_waitcnt lgkmcnt(0)
	v_add_f32_e32 v148, v148, v149
	ds_bpermute_b32 v149, v169, v148
	s_waitcnt lgkmcnt(0)
	v_add_f32_e32 v148, v148, v149
	ds_bpermute_b32 v149, v170, v148
	s_waitcnt lgkmcnt(0)
	v_add_f32_e32 v148, v148, v149
	ds_bpermute_b32 v149, v171, v148
	s_waitcnt lgkmcnt(0)
	v_add_f32_e32 v148, v148, v149
	ds_bpermute_b32 v149, v172, v148
	s_waitcnt lgkmcnt(0)
	v_add_f32_e32 v148, v148, v149
	ds_bpermute_b32 v149, v173, v148
	s_waitcnt lgkmcnt(0)
	v_add_f32_e32 v148, v148, v149
	v_fmamk_f32 v148, v148, 0x3a000000, v174
	v_mul_f32_e32 v149, 0x4b800000, v148
	v_cmp_gt_f32_e32 vcc, s42, v148
	s_nop 1
	v_cndmask_b32_e32 v148, v148, v149, vcc
	v_rsq_f32_e32 v158, v148
	v_lshl_add_u64 v[148:149], v[162:163], 0, s[26:27]
	v_mul_f32_e32 v159, 0x45800000, v158
	v_cndmask_b32_e32 v158, v158, v159, vcc
	v_pk_mul_f32 v[144:145], v[158:159], v[144:145] op_sel_hi:[0,1]
	v_pk_mul_f32 v[146:147], v[158:159], v[146:147] op_sel_hi:[0,1]
	v_pk_mul_f32 v[144:145], v[28:29], v[144:145]
	v_pk_mul_f32 v[146:147], v[30:31], v[146:147]
	global_store_dwordx4 v[148:149], v[144:147], off nt
	s_nop 1
	v_pk_mul_f32 v[144:145], v[158:159], v[150:151] op_sel_hi:[0,1]
	v_pk_mul_f32 v[146:147], v[158:159], v[152:153] op_sel_hi:[0,1]
	v_pk_mul_f32 v[144:145], v[144:145], v[24:25]
	v_pk_mul_f32 v[146:147], v[146:147], v[26:27]
	global_store_dwordx4 v[148:149], v[144:147], off offset:16 nt
	s_nop 1
	v_pk_mul_f32 v[144:145], v[158:159], v[154:155] op_sel_hi:[0,1]
	v_pk_mul_f32 v[146:147], v[158:159], v[156:157] op_sel_hi:[0,1]
	v_pk_mul_f32 v[144:145], v[20:21], v[144:145]
	v_pk_mul_f32 v[146:147], v[22:23], v[146:147]
	global_store_dwordx4 v[148:149], v[144:147], off offset:2048 nt
	s_nop 1
	v_pk_mul_f32 v[144:145], v[158:159], v[176:177] op_sel_hi:[0,1]
	v_pk_mul_f32 v[146:147], v[158:159], v[178:179] op_sel_hi:[0,1]
	v_pk_mul_f32 v[144:145], v[144:145], v[16:17]
	v_pk_mul_f32 v[146:147], v[146:147], v[18:19]
	global_store_dwordx4 v[148:149], v[144:147], off offset:2064 nt
	v_add_co_u32_e32 v148, vcc, s33, v148
	s_nop 0
	v_pk_mul_f32 v[144:145], v[158:159], v[180:181] op_sel_hi:[0,1]
	v_pk_mul_f32 v[146:147], v[158:159], v[184:185] op_sel_hi:[0,1]
	v_pk_mul_f32 v[146:147], v[6:7], v[146:147]
	v_pk_mul_f32 v[144:145], v[4:5], v[144:145]
	v_addc_co_u32_e32 v149, vcc, 0, v149, vcc
	global_store_dwordx4 v[148:149], v[144:147], off nt
	s_nop 1
	v_pk_mul_f32 v[144:145], v[158:159], v[188:189] op_sel_hi:[0,1]
	v_pk_mul_f32 v[146:147], v[158:159], v[190:191] op_sel_hi:[0,1]
	v_pk_mul_f32 v[144:145], v[144:145], v[12:13]
	v_pk_mul_f32 v[146:147], v[146:147], v[14:15]
	global_store_dwordx4 v[148:149], v[144:147], off offset:16 nt
	s_nop 1
	v_pk_mul_f32 v[144:145], v[158:159], v[192:193] op_sel_hi:[0,1]
	v_pk_mul_f32 v[146:147], v[158:159], v[194:195] op_sel_hi:[0,1]
	v_pk_mul_f32 v[146:147], v[10:11], v[146:147]
	v_pk_mul_f32 v[144:145], v[8:9], v[144:145]
	global_store_dwordx4 v[148:149], v[144:147], off offset:2048 nt
	s_nop 1
	v_pk_mul_f32 v[144:145], v[158:159], v[198:199] op_sel_hi:[0,1]
	v_pk_mul_f32 v[146:147], v[158:159], v[200:201] op_sel_hi:[0,1]
	v_pk_mul_f32 v[146:147], v[146:147], v[2:3]
	v_pk_mul_f32 v[144:145], v[144:145], v[0:1]
	global_store_dwordx4 v[148:149], v[144:147], off offset:2064 nt
	s_andn2_b64 vcc, exec, s[24:25]
	s_cbranch_vccz .LBB0_1160

.LBB0_1167:
	v_and_b32_e32 v145, 0xffff0000, v92
	v_and_b32_e32 v147, 0xffff0000, v93
	v_lshlrev_b32_e32 v144, 16, v92
	v_lshlrev_b32_e32 v146, 16, v93
	v_mov_b32_e32 v150, v145
	v_mov_b32_e32 v151, v147
	v_mov_b32_e32 v148, v144
	v_mov_b32_e32 v149, v146
	v_pk_mul_f32 v[150:151], v[150:151], v[150:151]
	v_and_b32_e32 v153, 0xffff0000, v95
	v_pk_fma_f32 v[148:149], v[148:149], v[148:149], v[150:151]
	v_and_b32_e32 v151, 0xffff0000, v94
	v_lshlrev_b32_e32 v150, 16, v94
	v_lshlrev_b32_e32 v152, 16, v95
	v_mov_b32_e32 v156, v153
	v_mov_b32_e32 v157, v151
	v_mov_b32_e32 v154, v152
	v_mov_b32_e32 v155, v150
	v_pk_mul_f32 v[156:157], v[156:157], v[156:157]
	v_pk_add_f32 v[148:149], v[148:149], v[148:149] op_sel:[0,1] op_sel_hi:[1,0]
	v_pk_fma_f32 v[154:155], v[154:155], v[154:155], v[156:157]
	v_and_b32_e32 v157, 0xffff0000, v89
	v_pk_add_f32 v[148:149], v[154:155], v[148:149] op_sel:[1,0] op_sel_hi:[0,1]
	v_pk_add_f32 v[148:149], v[154:155], v[148:149]
	v_and_b32_e32 v155, 0xffff0000, v88
	v_lshlrev_b32_e32 v154, 16, v88
	v_lshlrev_b32_e32 v156, 16, v89
	v_mov_b32_e32 v176, v155
	v_mov_b32_e32 v177, v157
	v_mov_b32_e32 v158, v154
	v_mov_b32_e32 v159, v156
	v_pk_mul_f32 v[176:177], v[176:177], v[176:177]
	v_and_b32_e32 v179, 0xffff0000, v91
	v_pk_fma_f32 v[158:159], v[158:159], v[158:159], v[176:177]
	v_and_b32_e32 v177, 0xffff0000, v90
	v_lshlrev_b32_e32 v176, 16, v90
	v_lshlrev_b32_e32 v178, 16, v91
	v_mov_b32_e32 v182, v179
	v_mov_b32_e32 v183, v177
	v_mov_b32_e32 v180, v178
	v_mov_b32_e32 v181, v176
	v_pk_mul_f32 v[182:183], v[182:183], v[182:183]
	v_pk_add_f32 v[158:159], v[158:159], v[158:159] op_sel:[0,1] op_sel_hi:[1,0]
	v_pk_fma_f32 v[180:181], v[180:181], v[180:181], v[182:183]
	v_and_b32_e32 v185, 0xffff0000, v85
	v_pk_add_f32 v[158:159], v[180:181], v[158:159] op_sel:[1,0] op_sel_hi:[0,1]
	v_pk_add_f32 v[158:159], v[180:181], v[158:159]
	v_and_b32_e32 v181, 0xffff0000, v84
	v_lshlrev_b32_e32 v180, 16, v84
	v_mul_f32_e32 v182, v181, v181
	v_lshlrev_b32_e32 v184, 16, v85
	v_mul_f32_e32 v186, v185, v185
	v_and_b32_e32 v189, 0xffff0000, v86
	v_and_b32_e32 v193, 0xffff0000, v80
	v_lshlrev_b32_e32 v194, 16, v81
	v_and_b32_e32 v195, 0xffff0000, v81
	v_pk_fma_f32 v[182:183], v[180:181], v[180:181], v[182:183] op_sel_hi:[1,1,0]
	v_pk_fma_f32 v[186:187], v[184:185], v[184:185], v[186:187] op_sel_hi:[1,1,0]
	v_lshlrev_b32_e32 v188, 16, v86
	v_and_b32_e32 v191, 0xffff0000, v87
	v_lshlrev_b32_e32 v192, 16, v80
	v_pk_mul_f32 v[196:197], v[194:195], v[194:195]
	v_and_b32_e32 v199, 0xffff0000, v82
	v_mov_b32_e32 v206, v189
	v_mov_b32_e32 v207, v193
	v_lshlrev_b32_e32 v190, 16, v87
	v_lshlrev_b32_e32 v198, 16, v82
	v_lshlrev_b32_e32 v200, 16, v83
	v_and_b32_e32 v201, 0xffff0000, v83
	v_mov_b32_e32 v204, v188
	v_mov_b32_e32 v205, v192
	v_pk_mul_f32 v[206:207], v[206:207], v[206:207]
	v_mov_b32_e32 v183, v196
	v_mov_b32_e32 v187, v197
	v_mov_b32_e32 v196, v191
	v_mov_b32_e32 v197, v199
	v_pk_mul_f32 v[202:203], v[200:201], v[200:201]
	v_pk_fma_f32 v[204:205], v[204:205], v[204:205], v[206:207]
	v_pk_add_f32 v[182:183], v[182:183], v[186:187]
	v_mov_b32_e32 v186, v190
	v_mov_b32_e32 v187, v198
	v_pk_mul_f32 v[196:197], v[196:197], v[196:197]
	v_pk_add_f32 v[182:183], v[204:205], v[182:183]
	v_pk_fma_f32 v[186:187], v[186:187], v[186:187], v[196:197]
	v_mov_b32_e32 v149, v202
	v_mov_b32_e32 v159, v203
	v_pk_add_f32 v[182:183], v[186:187], v[182:183]
	v_pk_add_f32 v[148:149], v[148:149], v[158:159]
	s_ashr_i32 s19, s18, 31
	v_pk_add_f32 v[148:149], v[148:149], v[182:183]
	s_lshl_b64 s[18:19], s[18:19], 13
	v_add_f32_e32 v148, v148, v149
	ds_bpermute_b32 v149, v168, v148
	s_waitcnt lgkmcnt(0)
	v_add_f32_e32 v148, v148, v149
	ds_bpermute_b32 v149, v169, v148
	s_waitcnt lgkmcnt(0)
	v_add_f32_e32 v148, v148, v149
	ds_bpermute_b32 v149, v170, v148
	s_waitcnt lgkmcnt(0)
	v_add_f32_e32 v148, v148, v149
	ds_bpermute_b32 v149, v171, v148
	s_waitcnt lgkmcnt(0)
	v_add_f32_e32 v148, v148, v149
	ds_bpermute_b32 v149, v172, v148
	s_waitcnt lgkmcnt(0)
	v_add_f32_e32 v148, v148, v149
	ds_bpermute_b32 v149, v173, v148
	s_waitcnt lgkmcnt(0)
	v_add_f32_e32 v148, v148, v149
	v_fmamk_f32 v148, v148, 0x3a000000, v174
	v_mul_f32_e32 v149, 0x4b800000, v148
	v_cmp_gt_f32_e32 vcc, s42, v148
	s_nop 1
	v_cndmask_b32_e32 v148, v148, v149, vcc
	v_rsq_f32_e32 v158, v148
	v_lshl_add_u64 v[148:149], v[162:163], 0, s[18:19]
	v_mul_f32_e32 v159, 0x45800000, v158
	v_cndmask_b32_e32 v158, v158, v159, vcc
	v_pk_mul_f32 v[144:145], v[158:159], v[144:145] op_sel_hi:[0,1]
	v_pk_mul_f32 v[146:147], v[158:159], v[146:147] op_sel_hi:[0,1]
	v_pk_mul_f32 v[144:145], v[28:29], v[144:145]
	v_pk_mul_f32 v[146:147], v[30:31], v[146:147]
	global_store_dwordx4 v[148:149], v[144:147], off nt
	s_nop 1
	v_pk_mul_f32 v[144:145], v[158:159], v[150:151] op_sel_hi:[0,1]
	v_pk_mul_f32 v[146:147], v[158:159], v[152:153] op_sel_hi:[0,1]
	v_pk_mul_f32 v[144:145], v[144:145], v[24:25]
	v_pk_mul_f32 v[146:147], v[146:147], v[26:27]
	global_store_dwordx4 v[148:149], v[144:147], off offset:16 nt
	s_nop 1
	v_pk_mul_f32 v[144:145], v[158:159], v[154:155] op_sel_hi:[0,1]
	v_pk_mul_f32 v[146:147], v[158:159], v[156:157] op_sel_hi:[0,1]
	v_pk_mul_f32 v[144:145], v[20:21], v[144:145]
	v_pk_mul_f32 v[146:147], v[22:23], v[146:147]
	global_store_dwordx4 v[148:149], v[144:147], off offset:2048 nt
	s_nop 1
	v_pk_mul_f32 v[144:145], v[158:159], v[176:177] op_sel_hi:[0,1]
	v_pk_mul_f32 v[146:147], v[158:159], v[178:179] op_sel_hi:[0,1]
	v_pk_mul_f32 v[144:145], v[144:145], v[16:17]
	v_pk_mul_f32 v[146:147], v[146:147], v[18:19]
	global_store_dwordx4 v[148:149], v[144:147], off offset:2064 nt
	v_add_co_u32_e32 v148, vcc, s33, v148
	s_nop 0
	v_pk_mul_f32 v[144:145], v[158:159], v[180:181] op_sel_hi:[0,1]
	v_pk_mul_f32 v[146:147], v[158:159], v[184:185] op_sel_hi:[0,1]
	v_pk_mul_f32 v[146:147], v[6:7], v[146:147]
	v_pk_mul_f32 v[144:145], v[4:5], v[144:145]
	v_addc_co_u32_e32 v149, vcc, 0, v149, vcc
	global_store_dwordx4 v[148:149], v[144:147], off nt
	s_nop 1
	v_pk_mul_f32 v[144:145], v[158:159], v[188:189] op_sel_hi:[0,1]
	v_pk_mul_f32 v[146:147], v[158:159], v[190:191] op_sel_hi:[0,1]
	v_pk_mul_f32 v[144:145], v[144:145], v[12:13]
	v_pk_mul_f32 v[146:147], v[146:147], v[14:15]
	global_store_dwordx4 v[148:149], v[144:147], off offset:16 nt
	s_nop 1
	v_pk_mul_f32 v[144:145], v[158:159], v[192:193] op_sel_hi:[0,1]
	v_pk_mul_f32 v[146:147], v[158:159], v[194:195] op_sel_hi:[0,1]
	v_pk_mul_f32 v[146:147], v[10:11], v[146:147]
	v_pk_mul_f32 v[144:145], v[8:9], v[144:145]
	global_store_dwordx4 v[148:149], v[144:147], off offset:2048 nt
	s_nop 1
	v_pk_mul_f32 v[144:145], v[158:159], v[198:199] op_sel_hi:[0,1]
	v_pk_mul_f32 v[146:147], v[158:159], v[200:201] op_sel_hi:[0,1]
	v_pk_mul_f32 v[146:147], v[146:147], v[2:3]
	v_pk_mul_f32 v[144:145], v[144:145], v[0:1]
	global_store_dwordx4 v[148:149], v[144:147], off offset:2064 nt
	s_andn2_b64 vcc, exec, s[16:17]
	s_cbranch_vccz .LBB0_1162

.LBB0_1169:
	v_and_b32_e32 v145, 0xffff0000, v60
	v_and_b32_e32 v147, 0xffff0000, v61
	v_lshlrev_b32_e32 v144, 16, v60
	v_lshlrev_b32_e32 v146, 16, v61
	v_mov_b32_e32 v150, v145
	v_mov_b32_e32 v151, v147
	v_mov_b32_e32 v148, v144
	v_mov_b32_e32 v149, v146
	v_pk_mul_f32 v[150:151], v[150:151], v[150:151]
	v_and_b32_e32 v153, 0xffff0000, v63
	v_pk_fma_f32 v[148:149], v[148:149], v[148:149], v[150:151]
	v_and_b32_e32 v151, 0xffff0000, v62
	v_lshlrev_b32_e32 v150, 16, v62
	v_lshlrev_b32_e32 v152, 16, v63
	v_mov_b32_e32 v156, v153
	v_mov_b32_e32 v157, v151
	v_mov_b32_e32 v154, v152
	v_mov_b32_e32 v155, v150
	v_pk_mul_f32 v[156:157], v[156:157], v[156:157]
	v_pk_add_f32 v[148:149], v[148:149], v[148:149] op_sel:[0,1] op_sel_hi:[1,0]
	v_pk_fma_f32 v[154:155], v[154:155], v[154:155], v[156:157]
	v_and_b32_e32 v157, 0xffff0000, v57
	v_pk_add_f32 v[148:149], v[154:155], v[148:149] op_sel:[1,0] op_sel_hi:[0,1]
	v_pk_add_f32 v[148:149], v[154:155], v[148:149]
	v_and_b32_e32 v155, 0xffff0000, v56
	v_lshlrev_b32_e32 v154, 16, v56
	v_lshlrev_b32_e32 v156, 16, v57
	v_mov_b32_e32 v176, v155
	v_mov_b32_e32 v177, v157
	v_mov_b32_e32 v158, v154
	v_mov_b32_e32 v159, v156
	v_pk_mul_f32 v[176:177], v[176:177], v[176:177]
	v_and_b32_e32 v179, 0xffff0000, v59
	v_pk_fma_f32 v[158:159], v[158:159], v[158:159], v[176:177]
	v_and_b32_e32 v177, 0xffff0000, v58
	v_lshlrev_b32_e32 v176, 16, v58
	v_lshlrev_b32_e32 v178, 16, v59
	v_mov_b32_e32 v182, v179
	v_mov_b32_e32 v183, v177
	v_mov_b32_e32 v180, v178
	v_mov_b32_e32 v181, v176
	v_pk_mul_f32 v[182:183], v[182:183], v[182:183]
	v_pk_add_f32 v[158:159], v[158:159], v[158:159] op_sel:[0,1] op_sel_hi:[1,0]
	v_pk_fma_f32 v[180:181], v[180:181], v[180:181], v[182:183]
	v_and_b32_e32 v185, 0xffff0000, v53
	v_pk_add_f32 v[158:159], v[180:181], v[158:159] op_sel:[1,0] op_sel_hi:[0,1]
	v_pk_add_f32 v[158:159], v[180:181], v[158:159]
	v_and_b32_e32 v181, 0xffff0000, v52
	v_lshlrev_b32_e32 v180, 16, v52
	v_mul_f32_e32 v182, v181, v181
	v_lshlrev_b32_e32 v184, 16, v53
	v_mul_f32_e32 v186, v185, v185
	v_and_b32_e32 v189, 0xffff0000, v54
	v_and_b32_e32 v193, 0xffff0000, v48
	v_lshlrev_b32_e32 v194, 16, v49
	v_and_b32_e32 v195, 0xffff0000, v49
	v_pk_fma_f32 v[182:183], v[180:181], v[180:181], v[182:183] op_sel_hi:[1,1,0]
	v_pk_fma_f32 v[186:187], v[184:185], v[184:185], v[186:187] op_sel_hi:[1,1,0]
	v_lshlrev_b32_e32 v188, 16, v54
	v_and_b32_e32 v191, 0xffff0000, v55
	v_lshlrev_b32_e32 v192, 16, v48
	v_pk_mul_f32 v[196:197], v[194:195], v[194:195]
	v_and_b32_e32 v199, 0xffff0000, v50
	v_mov_b32_e32 v206, v189
	v_mov_b32_e32 v207, v193
	v_lshlrev_b32_e32 v190, 16, v55
	v_lshlrev_b32_e32 v198, 16, v50
	v_lshlrev_b32_e32 v200, 16, v51
	v_and_b32_e32 v201, 0xffff0000, v51
	v_mov_b32_e32 v204, v188
	v_mov_b32_e32 v205, v192
	v_pk_mul_f32 v[206:207], v[206:207], v[206:207]
	v_mov_b32_e32 v183, v196
	v_mov_b32_e32 v187, v197
	v_mov_b32_e32 v196, v191
	v_mov_b32_e32 v197, v199
	v_pk_mul_f32 v[202:203], v[200:201], v[200:201]
	v_pk_fma_f32 v[204:205], v[204:205], v[204:205], v[206:207]
	v_pk_add_f32 v[182:183], v[182:183], v[186:187]
	v_mov_b32_e32 v186, v190
	v_mov_b32_e32 v187, v198
	v_pk_mul_f32 v[196:197], v[196:197], v[196:197]
	v_pk_add_f32 v[182:183], v[204:205], v[182:183]
	v_pk_fma_f32 v[186:187], v[186:187], v[186:187], v[196:197]
	v_mov_b32_e32 v149, v202
	v_mov_b32_e32 v159, v203
	v_pk_add_f32 v[182:183], v[186:187], v[182:183]
	v_pk_add_f32 v[148:149], v[148:149], v[158:159]
	s_ashr_i32 s11, s10, 31
	v_pk_add_f32 v[148:149], v[148:149], v[182:183]
	s_lshl_b64 s[10:11], s[10:11], 13
	v_add_f32_e32 v148, v148, v149
	ds_bpermute_b32 v149, v168, v148
	s_waitcnt lgkmcnt(0)
	v_add_f32_e32 v148, v148, v149
	ds_bpermute_b32 v149, v169, v148
	s_waitcnt lgkmcnt(0)
	v_add_f32_e32 v148, v148, v149
	ds_bpermute_b32 v149, v170, v148
	s_waitcnt lgkmcnt(0)
	v_add_f32_e32 v148, v148, v149
	ds_bpermute_b32 v149, v171, v148
	s_waitcnt lgkmcnt(0)
	v_add_f32_e32 v148, v148, v149
	ds_bpermute_b32 v149, v172, v148
	s_waitcnt lgkmcnt(0)
	v_add_f32_e32 v148, v148, v149
	ds_bpermute_b32 v149, v173, v148
	s_waitcnt lgkmcnt(0)
	v_add_f32_e32 v148, v148, v149
	v_fmamk_f32 v148, v148, 0x3a000000, v174
	v_mul_f32_e32 v149, 0x4b800000, v148
	v_cmp_gt_f32_e32 vcc, s42, v148
	s_nop 1
	v_cndmask_b32_e32 v148, v148, v149, vcc
	v_rsq_f32_e32 v158, v148
	v_lshl_add_u64 v[148:149], v[162:163], 0, s[10:11]
	v_mul_f32_e32 v159, 0x45800000, v158
	v_cndmask_b32_e32 v158, v158, v159, vcc
	v_pk_mul_f32 v[144:145], v[158:159], v[144:145] op_sel_hi:[0,1]
	v_pk_mul_f32 v[146:147], v[158:159], v[146:147] op_sel_hi:[0,1]
	v_pk_mul_f32 v[144:145], v[28:29], v[144:145]
	v_pk_mul_f32 v[146:147], v[30:31], v[146:147]
	global_store_dwordx4 v[148:149], v[144:147], off nt
	s_nop 1
	v_pk_mul_f32 v[144:145], v[158:159], v[150:151] op_sel_hi:[0,1]
	v_pk_mul_f32 v[146:147], v[158:159], v[152:153] op_sel_hi:[0,1]
	v_pk_mul_f32 v[144:145], v[144:145], v[24:25]
	v_pk_mul_f32 v[146:147], v[146:147], v[26:27]
	global_store_dwordx4 v[148:149], v[144:147], off offset:16 nt
	s_nop 1
	v_pk_mul_f32 v[144:145], v[158:159], v[154:155] op_sel_hi:[0,1]
	v_pk_mul_f32 v[146:147], v[158:159], v[156:157] op_sel_hi:[0,1]
	v_pk_mul_f32 v[144:145], v[20:21], v[144:145]
	v_pk_mul_f32 v[146:147], v[22:23], v[146:147]
	global_store_dwordx4 v[148:149], v[144:147], off offset:2048 nt
	s_nop 1
	v_pk_mul_f32 v[144:145], v[158:159], v[176:177] op_sel_hi:[0,1]
	v_pk_mul_f32 v[146:147], v[158:159], v[178:179] op_sel_hi:[0,1]
	v_pk_mul_f32 v[144:145], v[144:145], v[16:17]
	v_pk_mul_f32 v[146:147], v[146:147], v[18:19]
	global_store_dwordx4 v[148:149], v[144:147], off offset:2064 nt
	v_add_co_u32_e32 v148, vcc, s33, v148
	s_nop 0
	v_pk_mul_f32 v[144:145], v[158:159], v[180:181] op_sel_hi:[0,1]
	v_pk_mul_f32 v[146:147], v[158:159], v[184:185] op_sel_hi:[0,1]
	v_pk_mul_f32 v[146:147], v[6:7], v[146:147]
	v_pk_mul_f32 v[144:145], v[4:5], v[144:145]
	v_addc_co_u32_e32 v149, vcc, 0, v149, vcc
	global_store_dwordx4 v[148:149], v[144:147], off nt
	s_nop 1
	v_pk_mul_f32 v[144:145], v[158:159], v[188:189] op_sel_hi:[0,1]
	v_pk_mul_f32 v[146:147], v[158:159], v[190:191] op_sel_hi:[0,1]
	v_pk_mul_f32 v[144:145], v[144:145], v[12:13]
	v_pk_mul_f32 v[146:147], v[146:147], v[14:15]
	global_store_dwordx4 v[148:149], v[144:147], off offset:16 nt
	s_nop 1
	v_pk_mul_f32 v[144:145], v[158:159], v[192:193] op_sel_hi:[0,1]
	v_pk_mul_f32 v[146:147], v[158:159], v[194:195] op_sel_hi:[0,1]
	v_pk_mul_f32 v[146:147], v[10:11], v[146:147]
	v_pk_mul_f32 v[144:145], v[8:9], v[144:145]
	global_store_dwordx4 v[148:149], v[144:147], off offset:2048 nt
	s_nop 1
	v_pk_mul_f32 v[144:145], v[158:159], v[198:199] op_sel_hi:[0,1]
	v_pk_mul_f32 v[146:147], v[158:159], v[200:201] op_sel_hi:[0,1]
	v_pk_mul_f32 v[146:147], v[146:147], v[2:3]
	v_pk_mul_f32 v[144:145], v[144:145], v[0:1]
	global_store_dwordx4 v[148:149], v[144:147], off offset:2064 nt
	s_andn2_b64 vcc, exec, s[8:9]
	s_cbranch_vccnz .LBB0_1142
.LBB0_1170:
	v_and_b32_e32 v145, 0xffff0000, v44
	v_and_b32_e32 v147, 0xffff0000, v45
	v_lshlrev_b32_e32 v144, 16, v44
	v_lshlrev_b32_e32 v146, 16, v45
	v_mov_b32_e32 v150, v145
	v_mov_b32_e32 v151, v147
	v_mov_b32_e32 v148, v144
	v_mov_b32_e32 v149, v146
	v_pk_mul_f32 v[150:151], v[150:151], v[150:151]
	v_and_b32_e32 v153, 0xffff0000, v47
	v_pk_fma_f32 v[148:149], v[148:149], v[148:149], v[150:151]
	v_and_b32_e32 v151, 0xffff0000, v46
	v_lshlrev_b32_e32 v150, 16, v46
	v_lshlrev_b32_e32 v152, 16, v47
	v_mov_b32_e32 v156, v153
	v_mov_b32_e32 v157, v151
	v_mov_b32_e32 v154, v152
	v_mov_b32_e32 v155, v150
	v_pk_mul_f32 v[156:157], v[156:157], v[156:157]
	v_pk_add_f32 v[148:149], v[148:149], v[148:149] op_sel:[0,1] op_sel_hi:[1,0]
	v_pk_fma_f32 v[154:155], v[154:155], v[154:155], v[156:157]
	v_and_b32_e32 v157, 0xffff0000, v41
	v_pk_add_f32 v[148:149], v[154:155], v[148:149] op_sel:[1,0] op_sel_hi:[0,1]
	v_pk_add_f32 v[148:149], v[154:155], v[148:149]
	v_and_b32_e32 v155, 0xffff0000, v40
	v_lshlrev_b32_e32 v154, 16, v40
	v_lshlrev_b32_e32 v156, 16, v41
	v_mov_b32_e32 v176, v155
	v_mov_b32_e32 v177, v157
	v_mov_b32_e32 v158, v154
	v_mov_b32_e32 v159, v156
	v_pk_mul_f32 v[176:177], v[176:177], v[176:177]
	v_and_b32_e32 v179, 0xffff0000, v43
	v_pk_fma_f32 v[158:159], v[158:159], v[158:159], v[176:177]
	v_and_b32_e32 v177, 0xffff0000, v42
	v_lshlrev_b32_e32 v176, 16, v42
	v_lshlrev_b32_e32 v178, 16, v43
	v_mov_b32_e32 v182, v179
	v_mov_b32_e32 v183, v177
	v_mov_b32_e32 v180, v178
	v_mov_b32_e32 v181, v176
	v_pk_mul_f32 v[182:183], v[182:183], v[182:183]
	v_pk_add_f32 v[158:159], v[158:159], v[158:159] op_sel:[0,1] op_sel_hi:[1,0]
	v_pk_fma_f32 v[180:181], v[180:181], v[180:181], v[182:183]
	v_and_b32_e32 v185, 0xffff0000, v37
	v_pk_add_f32 v[158:159], v[180:181], v[158:159] op_sel:[1,0] op_sel_hi:[0,1]
	v_pk_add_f32 v[158:159], v[180:181], v[158:159]
	v_and_b32_e32 v181, 0xffff0000, v36
	v_lshlrev_b32_e32 v180, 16, v36
	v_mul_f32_e32 v182, v181, v181
	v_lshlrev_b32_e32 v184, 16, v37
	v_mul_f32_e32 v186, v185, v185
	v_and_b32_e32 v189, 0xffff0000, v38
	v_and_b32_e32 v193, 0xffff0000, v32
	v_lshlrev_b32_e32 v194, 16, v33
	v_and_b32_e32 v195, 0xffff0000, v33
	v_pk_fma_f32 v[182:183], v[180:181], v[180:181], v[182:183] op_sel_hi:[1,1,0]
	v_pk_fma_f32 v[186:187], v[184:185], v[184:185], v[186:187] op_sel_hi:[1,1,0]
	v_lshlrev_b32_e32 v188, 16, v38
	v_and_b32_e32 v191, 0xffff0000, v39
	v_lshlrev_b32_e32 v192, 16, v32
	v_pk_mul_f32 v[196:197], v[194:195], v[194:195]
	v_and_b32_e32 v199, 0xffff0000, v34
	v_mov_b32_e32 v206, v189
	v_mov_b32_e32 v207, v193
	v_lshlrev_b32_e32 v190, 16, v39
	v_lshlrev_b32_e32 v198, 16, v34
	v_lshlrev_b32_e32 v200, 16, v35
	v_and_b32_e32 v201, 0xffff0000, v35
	v_mov_b32_e32 v204, v188
	v_mov_b32_e32 v205, v192
	v_pk_mul_f32 v[206:207], v[206:207], v[206:207]
	v_mov_b32_e32 v183, v196
	v_mov_b32_e32 v187, v197
	v_mov_b32_e32 v196, v191
	v_mov_b32_e32 v197, v199
	v_pk_mul_f32 v[202:203], v[200:201], v[200:201]
	v_pk_fma_f32 v[204:205], v[204:205], v[204:205], v[206:207]
	v_pk_add_f32 v[182:183], v[182:183], v[186:187]
	v_mov_b32_e32 v186, v190
	v_mov_b32_e32 v187, v198
	v_pk_mul_f32 v[196:197], v[196:197], v[196:197]
	v_pk_add_f32 v[182:183], v[204:205], v[182:183]
	v_pk_fma_f32 v[186:187], v[186:187], v[186:187], v[196:197]
	v_mov_b32_e32 v149, v202
	v_mov_b32_e32 v159, v203
	v_pk_add_f32 v[182:183], v[186:187], v[182:183]
	v_pk_add_f32 v[148:149], v[148:149], v[158:159]
	s_ashr_i32 s7, s6, 31
	v_pk_add_f32 v[148:149], v[148:149], v[182:183]
	s_lshl_b64 s[6:7], s[6:7], 13
	v_add_f32_e32 v148, v148, v149
	ds_bpermute_b32 v149, v168, v148
	s_waitcnt lgkmcnt(0)
	v_add_f32_e32 v148, v148, v149
	ds_bpermute_b32 v149, v169, v148
	s_waitcnt lgkmcnt(0)
	v_add_f32_e32 v148, v148, v149
	ds_bpermute_b32 v149, v170, v148
	s_waitcnt lgkmcnt(0)
	v_add_f32_e32 v148, v148, v149
	ds_bpermute_b32 v149, v171, v148
	s_waitcnt lgkmcnt(0)
	v_add_f32_e32 v148, v148, v149
	ds_bpermute_b32 v149, v172, v148
	s_waitcnt lgkmcnt(0)
	v_add_f32_e32 v148, v148, v149
	ds_bpermute_b32 v149, v173, v148
	s_waitcnt lgkmcnt(0)
	v_add_f32_e32 v148, v148, v149
	v_fmamk_f32 v148, v148, 0x3a000000, v174
	v_mul_f32_e32 v149, 0x4b800000, v148
	v_cmp_gt_f32_e32 vcc, s42, v148
	s_nop 1
	v_cndmask_b32_e32 v148, v148, v149, vcc
	v_rsq_f32_e32 v158, v148
	v_lshl_add_u64 v[148:149], v[162:163], 0, s[6:7]
	v_mul_f32_e32 v159, 0x45800000, v158
	v_cndmask_b32_e32 v158, v158, v159, vcc
	v_pk_mul_f32 v[144:145], v[158:159], v[144:145] op_sel_hi:[0,1]
	v_pk_mul_f32 v[146:147], v[158:159], v[146:147] op_sel_hi:[0,1]
	v_pk_mul_f32 v[144:145], v[28:29], v[144:145]
	v_pk_mul_f32 v[146:147], v[30:31], v[146:147]
	global_store_dwordx4 v[148:149], v[144:147], off nt
	s_nop 1
	v_pk_mul_f32 v[144:145], v[158:159], v[150:151] op_sel_hi:[0,1]
	v_pk_mul_f32 v[146:147], v[158:159], v[152:153] op_sel_hi:[0,1]
	v_pk_mul_f32 v[144:145], v[144:145], v[24:25]
	v_pk_mul_f32 v[146:147], v[146:147], v[26:27]
	global_store_dwordx4 v[148:149], v[144:147], off offset:16 nt
	s_nop 1
	v_pk_mul_f32 v[144:145], v[158:159], v[154:155] op_sel_hi:[0,1]
	v_pk_mul_f32 v[146:147], v[158:159], v[156:157] op_sel_hi:[0,1]
	v_pk_mul_f32 v[144:145], v[20:21], v[144:145]
	v_pk_mul_f32 v[146:147], v[22:23], v[146:147]
	global_store_dwordx4 v[148:149], v[144:147], off offset:2048 nt
	s_nop 1
	v_pk_mul_f32 v[144:145], v[158:159], v[176:177] op_sel_hi:[0,1]
	v_pk_mul_f32 v[146:147], v[158:159], v[178:179] op_sel_hi:[0,1]
	v_pk_mul_f32 v[144:145], v[144:145], v[16:17]
	v_pk_mul_f32 v[146:147], v[146:147], v[18:19]
	global_store_dwordx4 v[148:149], v[144:147], off offset:2064 nt
	v_add_co_u32_e32 v148, vcc, s33, v148
	s_nop 0
	v_pk_mul_f32 v[144:145], v[158:159], v[180:181] op_sel_hi:[0,1]
	v_pk_mul_f32 v[146:147], v[158:159], v[184:185] op_sel_hi:[0,1]
	v_pk_mul_f32 v[146:147], v[6:7], v[146:147]
	v_pk_mul_f32 v[144:145], v[4:5], v[144:145]
	v_addc_co_u32_e32 v149, vcc, 0, v149, vcc
	global_store_dwordx4 v[148:149], v[144:147], off nt
	s_nop 1
	v_pk_mul_f32 v[144:145], v[158:159], v[188:189] op_sel_hi:[0,1]
	v_pk_mul_f32 v[146:147], v[158:159], v[190:191] op_sel_hi:[0,1]
	v_pk_mul_f32 v[144:145], v[144:145], v[12:13]
	v_pk_mul_f32 v[146:147], v[146:147], v[14:15]
	global_store_dwordx4 v[148:149], v[144:147], off offset:16 nt
	s_nop 1
	v_pk_mul_f32 v[144:145], v[158:159], v[192:193] op_sel_hi:[0,1]
	v_pk_mul_f32 v[146:147], v[158:159], v[194:195] op_sel_hi:[0,1]
	v_pk_mul_f32 v[146:147], v[10:11], v[146:147]
	v_pk_mul_f32 v[144:145], v[8:9], v[144:145]
	global_store_dwordx4 v[148:149], v[144:147], off offset:2048 nt
	s_nop 1
	v_pk_mul_f32 v[144:145], v[158:159], v[198:199] op_sel_hi:[0,1]
	v_pk_mul_f32 v[146:147], v[158:159], v[200:201] op_sel_hi:[0,1]
	v_pk_mul_f32 v[146:147], v[146:147], v[2:3]
	v_pk_mul_f32 v[144:145], v[144:145], v[0:1]
	global_store_dwordx4 v[148:149], v[144:147], off offset:2064 nt
	s_branch .LBB0_1142
